# HGRN scan: chunk outputs go through an LDS image; staging waves copy it out with 16-byte stores issued after their prefetch loads
# speedup vs baseline: 1.0230x; 1.0051x over previous
; DI void hgrn_scan_mfma(const Params& p, char* shm) {
;     ...
;     for (int u = bx; u < 128; u += gridDim.x) {
;         const int dir = u & 1, head = (u >> 1) & 7, b = u >> 4;
;         const unsigned char* Fb = P + (dir ? P_HF1 : P_HF0); bf16_t* Oo = dir ? (bf16_t*)(p.ws + WS_P + P_HOB) : (bf16_t*)(p.ws + WS_H);
;         f32x4 S[8];
; #pragma unroll
;         for (int kt = 0; kt < 8; ++kt) S[kt] = (f32x4){0.f, 0.f, 0.f, 0.f};
;         const int lt = tid >> 4, lp = tid & 15;
;         u32x4 ra0, ra1, ra2, ra3, ra4, rb0, rb1, rb2, rb3, rb4;
.LBB0_2416:
	s_or_b64 exec, exec, s[14:15]
	v_cndmask_b32_e64 v3, 0, 1, s[40:41]
	v_lshl_add_u64 v[142:143], s[0:1], 0, v[0:1]
	v_readfirstlane_b32 s14, v3
	s_lshl_b32 s55, s14, 3
	s_lshl_b32 s14, s31, 2
	s_and_b32 s56, s14, 0xe00
	s_and_b64 s[14:15], s[12:13], exec
	s_cselect_b32 s14, s72, 0x146da000
	s_add_u32 s14, s68, s14
	s_addc_u32 s15, s69, 0
	s_add_u32 s14, s14, s38
	s_addc_u32 s15, s15, 0
	v_lshl_add_u64 v[132:133], v[120:121], 1, s[14:15]
	s_mov_b64 s[78:79], s[14:15]
	s_and_b64 s[14:15], s[12:13], exec
	s_cselect_b32 s15, 0, -1
	s_cselect_b32 s14, s73, 0xfffffc00
	s_add_i32 s0, s54, s55
	s_mul_hi_i32 s1, s0, 0x48000
	s_mul_i32 s0, s0, 0x48000
	s_or_b32 s0, s0, s56
	v_mov_b32_e32 v44, 0
	s_mov_b32 s74, 0
	v_lshl_add_u64 v[128:129], v[116:117], 0, s[38:39]
	v_lshl_add_u64 v[130:131], v[118:119], 0, s[38:39]
	v_mul_hi_i32_i24_e32 v135, s14, v147
	v_mul_i32_i24_e32 v134, s14, v147
	s_lshl_b64 s[52:53], s[14:15], 5
	v_mul_hi_i32_i24_e32 v137, s14, v152
	v_mul_i32_i24_e32 v136, s14, v152
	v_mul_hi_i32_i24_e32 v139, s14, v153
	v_mul_i32_i24_e32 v138, s14, v153
	v_mul_hi_i32_i24_e32 v141, s14, v154
	v_mul_i32_i24_e32 v140, s14, v154
	v_lshl_add_u64 v[144:145], v[122:123], 0, s[0:1]
	s_movk_i32 s38, 0xffe0
	s_mov_b32 s76, 0
	v_mov_b32_e32 v45, v44
	v_mov_b32_e32 v46, v44
	v_mov_b32_e32 v47, v44
	v_mov_b32_e32 v48, v44
	v_mov_b32_e32 v49, v44
	v_mov_b32_e32 v50, v44
	v_mov_b32_e32 v51, v44
	v_mov_b32_e32 v52, v44
	v_mov_b32_e32 v53, v44
	v_mov_b32_e32 v54, v44
	v_mov_b32_e32 v55, v44
	v_mov_b32_e32 v56, v44
	v_mov_b32_e32 v57, v44
	v_mov_b32_e32 v58, v44
	v_mov_b32_e32 v59, v44
	v_mov_b32_e32 v60, v44
	v_mov_b32_e32 v61, v44
	v_mov_b32_e32 v62, v44
	v_mov_b32_e32 v63, v44
	v_mov_b32_e32 v64, v44
	v_mov_b32_e32 v65, v44
	v_mov_b32_e32 v66, v44
	v_mov_b32_e32 v67, v44
	v_mov_b32_e32 v72, v44
	v_mov_b32_e32 v73, v44
	v_mov_b32_e32 v74, v44
	v_mov_b32_e32 v75, v44
	v_mov_b32_e32 v68, v44
	v_mov_b32_e32 v69, v44
	v_mov_b32_e32 v70, v44
	v_mov_b32_e32 v71, v44
	s_cmp_lg_u32 s100, 0
	s_cbranch_scc1 .Lscanh_pro
	v_add_u32_e32 v195, 0x8000, v161
	v_add_u32_e32 v197, 0x9000, v161
	v_bfe_u32 v200, v252, 4, 2
	v_bfe_u32 v201, v252, 2, 2
	v_lshl_add_u32 v200, v200, 2, v201
	v_mul_u32_u24_e32 v199, 0x110, v200
	v_and_b32_e32 v201, 3, v252
	v_lshl_add_u32 v199, v201, 3, v199
	v_and_b32_e32 v198, -16, v120
	v_lshl_add_u32 v198, v198, 1, v199
	v_bfe_u32 v200, v252, 4, 2
	v_mul_u32_u24_e32 v196, 576, v200
	v_and_b32_e32 v200, 15, v252
	v_lshl_add_u32 v196, v200, 1, v196
	v_lshrrev_b32_e32 v202, 6, v252
	v_lshl_add_u32 v196, v202, 5, v196
	v_add_u32_e32 v196, 0x1a200, v196

; DI unsigned pack2(float lo, float hi) { const f32x2 v = (f32x2){lo, hi}; return __builtin_bit_cast(unsigned, __builtin_convertvector(v, bf16x2_t)); }
; DI void hgrn_scan_mfma(const Params& p, char* shm) {
;     ...
;               o0 = __builtin_amdgcn_mfma_f32_16x16x32_bf16(__builtin_bit_cast(bf16x8, (u32x4){pack2(sc00[0], sc00[1]), pack2(sc00[2], sc00[3]), 0u, 0u}), vf, o0, 0, 0, 0);
;               o1 = __builtin_amdgcn_mfma_f32_16x16x32_bf16(__builtin_bit_cast(bf16x8, (u32x4){pack2(sc01[0], sc01[1]), pack2(sc01[2], sc01[3]), pack2(sc11[0], sc11[1]), pack2(sc11[2], sc11[3])}), vf, o1, 0, 0, 0);
; #pragma unroll
;               for (int r = 0; r < 4; ++r) {
;                   const long rb_ = (long)HG_ROW(b, dir, ch * C), st_ = dir ? -(long)D : (long)D; bf16_t* op_ = Oo + rb_ * D + head * 128 + vcol + (long)(g * 4 + r) * st_;
;                   op_[0] = (bf16_t)(pack2(o0[r], 0.f) & 0xffffu); op_[16 * st_] = (bf16_t)(pack2(o1[r], 0.f) & 0xffffu); }
.LBB0_2429:
	ds_read_b128 v[80:83], v160 offset:17408
	ds_read_b128 v[76:79], v160
	ds_read_b128 v[84:87], v160 offset:21760
	ds_read_b128 v[88:91], v160 offset:17472
	ds_read_b128 v[92:95], v160 offset:64
	ds_read_b128 v[96:99], v160 offset:4352
	ds_read_b128 v[100:103], v160 offset:21824
	ds_read_b128 v[104:107], v160 offset:4416
	s_waitcnt lgkmcnt(6)
	v_mfma_f32_16x16x32_bf16 v[76:79], v[80:83], v[76:79], 0
	v_cvt_pk_bf16_f32 v186, v52, v53
	v_cvt_pk_bf16_f32 v187, v54, v55
	v_cvt_pk_bf16_f32 v188, v56, v57
	s_waitcnt lgkmcnt(3)
	v_mfma_f32_16x16x32_bf16 v[76:79], v[88:91], v[92:95], v[76:79]
	ds_read_b128 v[92:95], v160 offset:17536
	ds_read_b128 v[108:111], v160 offset:128
	v_cvt_pk_bf16_f32 v189, v58, v59
	s_cmp_lt_u32 s76, 8
	s_waitcnt lgkmcnt(4)
	v_mfma_f32_16x16x32_bf16 v[84:87], v[84:87], v[96:99], 0
	s_cselect_b32 s77, 0xff, s58
	s_add_i32 s77, s77, s38
	s_add_i32 s78, s77, 32
	s_waitcnt lgkmcnt(2)
	v_mfma_f32_16x16x32_bf16 v[84:87], v[100:103], v[104:107], v[84:87]
	ds_read_b128 v[100:103], v160 offset:21888
	ds_read_b128 v[162:165], v160 offset:17600
	ds_read_b128 v[166:169], v160 offset:192
	ds_read_b128 v[170:173], v160 offset:4480
	ds_read_b128 v[174:177], v160 offset:21952
	ds_read_b128 v[178:181], v160 offset:4544
	s_and_b64 s[14:15], s[12:13], exec
	s_waitcnt lgkmcnt(6)
	v_mfma_f32_16x16x32_bf16 v[108:111], v[92:95], v[108:111], v[76:79]
	ds_read_b64_tr_b16 v[76:77], v198 offset:8704
	ds_read_b64_tr_b16 v[78:79], v198 offset:13056
	v_mov_b32_e32 v0, s39
	s_waitcnt lgkmcnt(4)
	v_mfma_f32_16x16x32_bf16 v[84:87], v[100:103], v[170:173], v[84:87]
	v_add_u32_e32 v125, 0x1000, v161
	v_mfma_f32_16x16x32_bf16 v[100:103], v[162:165], v[166:169], v[108:111]
	ds_read2_b64 v[166:169], v125 offset0:32 offset1:36
	s_cselect_b32 s14, s74, s78
	ds_read2_b64 v[108:111], v161 offset1:4
	v_mfma_f32_16x16x32_bf16 v[80:83], v[80:83], v[96:99], 0
	s_nop 2
	s_nop 0
	v_cndmask_b32_e64 v0, v100, v0, s[4:5]
	v_cndmask_b32_e64 v0, v0, v100, s[6:7]
	v_cndmask_b32_e64 v3, v102, 0, s[8:9]
	s_waitcnt lgkmcnt(4)
	v_mfma_f32_16x16x32_bf16 v[84:87], v[174:177], v[178:181], v[84:87]
	v_cvt_pk_bf16_f32 v174, v44, v45
	v_cvt_pk_bf16_f32 v175, v46, v47
	v_cvt_pk_bf16_f32 v176, v48, v49
	v_cvt_pk_bf16_f32 v177, v50, v51
	v_mfma_f32_16x16x32_bf16 v[80:83], v[88:91], v[104:107], v[80:83]
	s_add_u32 s14, s50, s14
	s_addc_u32 s15, s51, 0
	s_lshl_b64 s[14:15], s[14:15], 11
	s_waitcnt lgkmcnt(0)
	v_mfma_f32_16x16x32_bf16 v[96:99], v[108:111], v[174:177], 0
	ds_read2_b64 v[108:111], v161 offset0:8 offset1:12
	ds_read2_b64 v[182:185], v125 offset0:40 offset1:44
	ds_read2_b64 v[88:91], v161 offset0:16 offset1:20
	ds_read2_b64 v[104:107], v125 offset0:48 offset1:52
	v_mfma_f32_16x16x32_bf16 v[166:169], v[166:169], v[174:177], 0
	v_cvt_pk_bf16_f32 v174, v60, v61
	v_cvt_pk_bf16_f32 v175, v62, v63
	v_cvt_pk_bf16_f32 v176, v64, v65
	s_waitcnt lgkmcnt(3)
	v_mfma_f32_16x16x32_bf16 v[96:99], v[108:111], v[186:189], v[96:99]
	v_cvt_pk_bf16_f32 v177, v66, v67
	v_mfma_f32_16x16x32_bf16 v[80:83], v[92:95], v[170:173], v[80:83]
	v_mov_b32_e32 v92, s39
	v_cndmask_b32_e64 v1, v84, v92, s[4:5]
	s_waitcnt lgkmcnt(2)
	v_mfma_f32_16x16x32_bf16 v[108:111], v[182:185], v[186:189], v[166:169]
	s_nop 2
	ds_read2_b64 v[166:169], v161 offset0:24 offset1:28
	ds_read2_b64 v[182:185], v125 offset0:56 offset1:60
	v_cvt_pk_bf16_f32 v186, v72, v73
	v_cvt_pk_bf16_f32 v187, v74, v75
	s_waitcnt lgkmcnt(3)
	v_mfma_f32_16x16x32_bf16 v[88:91], v[88:91], v[174:177], v[96:99]
	v_cvt_pk_bf16_f32 v188, v68, v69
	v_cvt_pk_bf16_f32 v189, v70, v71
	v_mfma_f32_16x16x32_bf16 v[80:83], v[162:165], v[178:181], v[80:83]
	v_cndmask_b32_e64 v96, v1, v84, s[6:7]
	v_cndmask_b32_e64 v1, 0, v101, s[6:7]
	v_cndmask_b32_e64 v84, v103, 0, s[10:11]
	s_waitcnt lgkmcnt(2)
	v_mfma_f32_16x16x32_bf16 v[92:95], v[104:107], v[174:177], v[108:111]
	v_cvt_pk_bf16_f32 v0, v0, v1
	v_cvt_pk_bf16_f32 v1, v3, v84
	v_mov_b32_e32 v3, v2
	v_cndmask_b32_e64 v97, 0, v85, s[6:7]
	v_cndmask_b32_e64 v98, v86, 0, s[8:9]
	v_cndmask_b32_e64 v99, v87, 0, s[10:11]
	s_waitcnt lgkmcnt(1)
	v_mfma_f32_16x16x32_bf16 v[88:91], v[166:169], v[186:189], v[88:91]
	v_cvt_pk_bf16_f32 v80, v80, v81
	v_cvt_pk_bf16_f32 v81, v82, v83
	v_cvt_pk_bf16_f32 v82, v96, v97
	v_cvt_pk_bf16_f32 v83, v98, v99
	s_waitcnt lgkmcnt(0)
	v_mfma_f32_16x16x32_bf16 v[92:95], v[182:185], v[186:189], v[92:95]
	v_mfma_f32_16x16x32_bf16 v[84:87], v[0:3], v[76:79], v[88:91]
	v_mfma_f32_16x16x32_bf16 v[80:83], v[80:83], v[76:79], v[92:95]
	s_nop 0
	s_nop 3
	s_nop 1
	v_cvt_pk_bf16_f32 v3, v84, s0
	ds_write_b16 v196, v3 offset:0
	v_cvt_pk_bf16_f32 v3, v80, s0
	ds_write_b16 v196, v3 offset:2304
	v_cvt_pk_bf16_f32 v3, v85, s0
	ds_write_b16 v196, v3 offset:144
	v_cvt_pk_bf16_f32 v3, v81, s0
	ds_write_b16 v196, v3 offset:2448
	v_cvt_pk_bf16_f32 v3, v86, s0
	ds_write_b16 v196, v3 offset:288
	ds_read_b64_tr_b16 v[200:201], v199 offset:17408
	ds_read_b64_tr_b16 v[202:203], v199 offset:21760
	ds_read_b64_tr_b16 v[204:205], v199 offset:17440
	ds_read_b64_tr_b16 v[206:207], v199 offset:21792
	ds_read_b64_tr_b16 v[208:209], v199 offset:17472
	ds_read_b64_tr_b16 v[210:211], v199 offset:21824
	ds_read_b64_tr_b16 v[212:213], v199 offset:17504
	ds_read_b64_tr_b16 v[214:215], v199 offset:21856
	ds_read_b64_tr_b16 v[216:217], v199 offset:17536
	ds_read_b64_tr_b16 v[218:219], v199 offset:21888
	ds_read_b64_tr_b16 v[220:221], v199 offset:17568
	ds_read_b64_tr_b16 v[222:223], v199 offset:21920
	ds_read_b64_tr_b16 v[224:225], v199 offset:17600
	ds_read_b64_tr_b16 v[226:227], v199 offset:21952
	ds_read_b64_tr_b16 v[228:229], v199 offset:17632
	ds_read_b64_tr_b16 v[230:231], v199 offset:21984
	s_waitcnt lgkmcnt(14)
	v_mfma_f32_16x16x32_bf16 v[44:47], v[200:203], v[76:79], v[44:47]
	v_cvt_pk_bf16_f32 v3, v82, s0
	ds_write_b16 v196, v3 offset:2592
	v_cvt_pk_bf16_f32 v3, v87, s0
	s_waitcnt lgkmcnt(13)
	v_mfma_f32_16x16x32_bf16 v[48:51], v[204:207], v[76:79], v[48:51]
	s_waitcnt lgkmcnt(11)
	v_mfma_f32_16x16x32_bf16 v[52:55], v[208:211], v[76:79], v[52:55]
	ds_write_b16 v196, v3 offset:432
	v_cvt_pk_bf16_f32 v3, v83, s0
	s_waitcnt lgkmcnt(10)
	v_mfma_f32_16x16x32_bf16 v[56:59], v[212:215], v[76:79], v[56:59]
	ds_write_b16 v196, v3 offset:2736
	s_waitcnt lgkmcnt(9)
	v_mfma_f32_16x16x32_bf16 v[60:63], v[216:219], v[76:79], v[60:63]
	ds_read_b128 v[108:111], v149 offset:26112
	ds_read_b128 v[104:107], v149 offset:26176
	ds_read_b128 v[100:103], v149 offset:26240
	ds_read_b128 v[96:99], v149 offset:26304
	s_waitcnt lgkmcnt(11)
	v_mfma_f32_16x16x32_bf16 v[64:67], v[220:223], v[76:79], v[64:67]
	s_waitcnt lgkmcnt(9)
	v_mfma_f32_16x16x32_bf16 v[80:83], v[224:227], v[76:79], v[72:75]
	ds_read_b128 v[92:95], v149 offset:26368
	ds_read_b128 v[88:91], v149 offset:26432
	ds_read_b128 v[84:87], v149 offset:26496
	ds_read_b128 v[72:75], v149 offset:26560
	s_waitcnt lgkmcnt(0)
	s_barrier
	v_mfma_f32_16x16x32_bf16 v[76:79], v[228:231], v[76:79], v[68:71]
	s_nop 0
	s_nop 0
	s_and_saveexec_b64 s[14:15], s[2:3]
	s_or_b64 exec, exec, s[14:15]
	s_andn2_b64 vcc, exec, s[56:57]
	s_branch .LBB0_2441
; DI unsigned pack2(float lo, float hi) { const f32x2 v = (f32x2){lo, hi}; return __builtin_bit_cast(unsigned, __builtin_convertvector(v, bf16x2_t)); }
; DI void hgrn_scan_mfma(const Params& p, char* shm) {
;     ...
;             { const bf16_t* kt16 = (const bf16_t*)KtL; const bf16_t* v16 = (const bf16_t*)VL; const int vcol = w * 16 + l15;
;     ...
;               const bf16x8 vf = __builtin_bit_cast(bf16x8, (u32x4){HG_U2(v16, g * 4 + 0, g * 4 + 1, vcol), HG_U2(v16, g * 4 + 2, g * 4 + 3, vcol), HG_U2(v16, 16 + g * 4 + 0, 16 + g * 4 + 1, vcol), HG_U2(v16, 16 + g * 4 + 2, 16 + g * 4 + 3, vcol)});
;               f32x4 sc00 = (f32x4){0.f, 0.f, 0.f, 0.f}, sc01 = sc00, sc11 = sc00, o0 = sc00, o1 = sc00;
; #pragma unroll
;               for (int kc = 0; kc < 4; ++kc) {
;                   const bf16x8 aK0 = *(const bf16x8*)(KtL + l15 * QS + kc * 64 + g * 16), aK1 = *(const bf16x8*)(KtL + (16 + l15) * QS + kc * 64 + g * 16);
;                   const bf16x8 bQ0 = *(const bf16x8*)(QtL + l15 * QS + kc * 64 + g * 16), bQ1 = *(const bf16x8*)(QtL + (16 + l15) * QS + kc * 64 + g * 16);
;                   sc00 = __builtin_amdgcn_mfma_f32_16x16x32_bf16(aK0, bQ0, sc00, 0, 0, 0);
;                   sc01 = __builtin_amdgcn_mfma_f32_16x16x32_bf16(aK0, bQ1, sc01, 0, 0, 0);
;                   sc11 = __builtin_amdgcn_mfma_f32_16x16x32_bf16(aK1, bQ1, sc11, 0, 0, 0);
;                   const int kp = kc;
;                   const u32x2 qa0 = *(const u32x2*)(QtL + l15 * QS + ((2 * kp) * 16 + g * 4) * 2), qb0 = *(const u32x2*)(QtL + l15 * QS + ((2 * kp + 1) * 16 + g * 4) * 2);
;                   const u32x2 qa1 = *(const u32x2*)(QtL + (16 + l15) * QS + ((2 * kp) * 16 + g * 4) * 2), qb1 = *(const u32x2*)(QtL + (16 + l15) * QS + ((2 * kp + 1) * 16 + g * 4) * 2);
;                   const bf16x8 sw = __builtin_bit_cast(bf16x8, (u32x4){pack2(S[2 * kp][0], S[2 * kp][1]), pack2(S[2 * kp][2], S[2 * kp][3]), pack2(S[2 * kp + 1][0], S[2 * kp + 1][1]), pack2(S[2 * kp + 1][2], S[2 * kp + 1][3])});
;                   o0 = __builtin_amdgcn_mfma_f32_16x16x32_bf16(__builtin_bit_cast(bf16x8, (u32x4){qa0.x, qa0.y, qb0.x, qb0.y}), sw, o0, 0, 0, 0);
;                   o1 = __builtin_amdgcn_mfma_f32_16x16x32_bf16(__builtin_bit_cast(bf16x8, (u32x4){qa1.x, qa1.y, qb1.x, qb1.y}), sw, o1, 0, 0, 0); }
; #pragma unroll
;               for (int r = 0; r < 4; ++r) if (g * 4 + r > l15) { sc00[r] = 0.f; sc11[r] = 0.f; }
.LBB0_2441:
	v_mul_f32_e32 v58, v98, v58
	v_mul_f32_e32 v59, v99, v59
	v_mul_f32_e32 v56, v96, v56
	v_mul_f32_e32 v57, v97, v57
	ds_read_b128 v[96:99], v160 offset:50176
	v_mul_f32_e32 v62, v94, v62
	v_mul_f32_e32 v63, v95, v63
	v_mul_f32_e32 v60, v92, v60
	v_mul_f32_e32 v61, v93, v61
	ds_read_b128 v[68:71], v160 offset:54528
	ds_read_b128 v[92:95], v160 offset:32768
	v_mul_f32_e32 v46, v110, v46
	v_mul_f32_e32 v47, v111, v47
	v_mul_f32_e32 v44, v108, v44
	v_mul_f32_e32 v45, v109, v45
	v_mul_f32_e32 v50, v106, v50
	v_mul_f32_e32 v51, v107, v51
	v_mul_f32_e32 v48, v104, v48
	v_mul_f32_e32 v49, v105, v49
	v_mul_f32_e32 v54, v102, v54
	v_mul_f32_e32 v55, v103, v55
	v_mul_f32_e32 v52, v100, v52
	v_mul_f32_e32 v53, v101, v53
	ds_read_b128 v[100:103], v160 offset:37120
	ds_read_b128 v[104:107], v160 offset:50240
	ds_read_b128 v[108:111], v160 offset:32832
	ds_read_b128 v[162:165], v160 offset:54592
	ds_read_b128 v[166:169], v160 offset:37184
	v_mul_f32_e32 v66, v90, v66
	v_mul_f32_e32 v67, v91, v67
	s_waitcnt lgkmcnt(5)
	v_mfma_f32_16x16x32_bf16 v[90:93], v[96:99], v[92:95], 0
	v_mul_f32_e64 v64, v88, v64
	v_mul_f32_e64 v65, v89, v65
	v_mul_f32_e32 v78, v74, v78
	v_mul_f32_e32 v79, v75, v79
	v_mul_f32_e32 v76, v72, v76
	v_mul_f32_e32 v77, v73, v77
	s_waitcnt lgkmcnt(4)
	v_mfma_f32_16x16x32_bf16 v[170:173], v[68:71], v[100:103], 0
	v_mul_f32_e64 v70, v86, v82
	v_mul_f32_e64 v71, v87, v83
	v_mul_f32_e32 v68, v84, v80
	v_mul_f32_e32 v69, v85, v81
	ds_read_b128 v[84:87], v160 offset:50304
	s_waitcnt lgkmcnt(3)
	v_mfma_f32_16x16x32_bf16 v[80:83], v[104:107], v[108:111], v[90:93]
	s_nop 2
	ds_read_b128 v[88:91], v160 offset:54656
	ds_read_b128 v[92:95], v160 offset:32896
	v_cvt_pk_bf16_f32 v186, v52, v53
	v_cvt_pk_bf16_f32 v187, v54, v55
	s_waitcnt lgkmcnt(3)
	v_mfma_f32_16x16x32_bf16 v[108:111], v[162:165], v[166:169], v[170:173]
	ds_read_b128 v[162:165], v160 offset:37248
	s_nop 1
	ds_read_b128 v[170:173], v160 offset:50368
	ds_read_b128 v[174:177], v160 offset:32960
	ds_read_b128 v[72:75], v160 offset:54720
	ds_read_b128 v[178:181], v160 offset:37312
	v_cvt_pk_bf16_f32 v188, v56, v57
	s_waitcnt lgkmcnt(4)
	v_mfma_f32_16x16x32_bf16 v[88:91], v[88:91], v[162:165], v[108:111]
	v_cvt_pk_bf16_f32 v189, v58, v59
	s_add_i32 s14, s74, 32
	s_and_b64 s[0:1], s[12:13], exec
	v_mfma_f32_16x16x32_bf16 v[92:95], v[84:87], v[92:95], v[80:83]
	ds_read_b64_tr_b16 v[80:81], v198 offset:41472
	ds_read_b64_tr_b16 v[82:83], v198 offset:45824
	ds_read2_b64 v[108:111], v195 offset1:4
	s_waitcnt lgkmcnt(3)
	v_mfma_f32_16x16x32_bf16 v[72:75], v[72:75], v[178:181], v[88:91]
	v_mov_b32_e32 v0, s39
	ds_read2_b64 v[88:91], v197 offset0:32 offset1:36
	v_mfma_f32_16x16x32_bf16 v[96:99], v[96:99], v[100:103], 0
	s_cselect_b32 s0, s14, s77
	s_add_u32 s0, s50, s0
	v_mfma_f32_16x16x32_bf16 v[92:95], v[170:173], v[174:177], v[92:95]
	v_cvt_pk_bf16_f32 v174, v44, v45
	v_cvt_pk_bf16_f32 v175, v46, v47
	v_cvt_pk_bf16_f32 v176, v48, v49
	v_cvt_pk_bf16_f32 v177, v50, v51
	v_mfma_f32_16x16x32_bf16 v[96:99], v[104:107], v[166:169], v[96:99]
	s_nop 2
	v_cndmask_b32_e64 v0, v92, v0, s[4:5]
	v_cndmask_b32_e64 v0, v0, v92, s[6:7]
	v_cndmask_b32_e64 v3, v94, 0, s[8:9]
	s_waitcnt lgkmcnt(1)
	v_mfma_f32_16x16x32_bf16 v[100:103], v[108:111], v[174:177], 0
	ds_read2_b64 v[108:111], v195 offset0:8 offset1:12
	ds_read2_b64 v[182:185], v197 offset0:40 offset1:44
	ds_read2_b64 v[104:107], v195 offset0:16 offset1:20
	ds_read2_b64 v[166:169], v197 offset0:48 offset1:52
	s_addc_u32 s1, s51, 0
	s_waitcnt lgkmcnt(4)
	v_mfma_f32_16x16x32_bf16 v[88:91], v[88:91], v[174:177], 0
	v_cvt_pk_bf16_f32 v174, v60, v61
	v_cvt_pk_bf16_f32 v175, v62, v63
	v_cvt_pk_bf16_f32 v176, v64, v65
	s_waitcnt lgkmcnt(3)
	v_mfma_f32_16x16x32_bf16 v[100:103], v[108:111], v[186:189], v[100:103]
	v_cvt_pk_bf16_f32 v177, v66, v67
	s_lshl_b64 s[0:1], s[0:1], 11
	v_mfma_f32_16x16x32_bf16 v[84:87], v[84:87], v[162:165], v[96:99]
	s_sub_i32 s38, s38, 64
	s_add_i32 s74, s74, 64
	s_and_b64 vcc, exec, s[54:55]
	s_waitcnt lgkmcnt(2)
	v_mfma_f32_16x16x32_bf16 v[88:91], v[182:185], v[186:189], v[88:91]
	ds_read2_b64 v[108:111], v195 offset0:24 offset1:28
	ds_read2_b64 v[182:185], v197 offset0:56 offset1:60
	v_cvt_pk_bf16_f32 v186, v68, v69
	v_cvt_pk_bf16_f32 v187, v70, v71
	s_waitcnt lgkmcnt(3)
	v_mfma_f32_16x16x32_bf16 v[96:99], v[104:107], v[174:177], v[100:103]
	v_cvt_pk_bf16_f32 v188, v76, v77
	v_cvt_pk_bf16_f32 v189, v78, v79
	s_nop 0
	v_mov_b32_e32 v100, s39
	v_mfma_f32_16x16x32_bf16 v[84:87], v[170:173], v[178:181], v[84:87]
	v_cndmask_b32_e64 v1, v72, v100, s[4:5]
	v_cndmask_b32_e64 v100, v1, v72, s[6:7]
	v_cndmask_b32_e64 v1, 0, v93, s[6:7]
	s_waitcnt lgkmcnt(2)
	v_mfma_f32_16x16x32_bf16 v[88:91], v[166:169], v[174:177], v[88:91]
	v_cndmask_b32_e64 v72, v95, 0, s[10:11]
	v_cvt_pk_bf16_f32 v0, v0, v1
	v_cvt_pk_bf16_f32 v1, v3, v72
	s_waitcnt lgkmcnt(1)
	v_mfma_f32_16x16x32_bf16 v[92:95], v[108:111], v[186:189], v[96:99]
	v_mov_b32_e32 v3, v2
	v_cvt_pk_bf16_f32 v84, v84, v85
	v_cvt_pk_bf16_f32 v85, v86, v87
	v_cndmask_b32_e64 v96, 0, v73, s[6:7]
	v_cndmask_b32_e64 v97, v74, 0, s[8:9]
	v_cndmask_b32_e64 v98, v75, 0, s[10:11]
	v_cvt_pk_bf16_f32 v86, v100, v96
	v_cvt_pk_bf16_f32 v87, v97, v98
	s_waitcnt lgkmcnt(0)
; DI unsigned pack2(float lo, float hi) { const f32x2 v = (f32x2){lo, hi}; return __builtin_bit_cast(unsigned, __builtin_convertvector(v, bf16x2_t)); }
; DI void hgrn_scan_mfma(const Params& p, char* shm) {
;     ...
; #pragma unroll
;               for (int r = 0; r < 4; ++r) {
;                   const long rb_ = (long)HG_ROW(b, dir, ch * C), st_ = dir ? -(long)D : (long)D; bf16_t* op_ = Oo + rb_ * D + head * 128 + vcol + (long)(g * 4 + r) * st_;
;                   op_[0] = (bf16_t)(pack2(o0[r], 0.f) & 0xffffu); op_[16 * st_] = (bf16_t)(pack2(o1[r], 0.f) & 0xffffu); }
; #pragma unroll
;               for (int kt = 0; kt < 8; ++kt) { const f32x4 dcy = *(const f32x4*)(eBL + kt * 16 + g * 4); const int kcol = kt * 16 + l15;
;                   const bf16x8 kl = __builtin_bit_cast(bf16x8, (u32x4){HG_U2(kt16, g * 4 + 0, g * 4 + 1, kcol), HG_U2(kt16, g * 4 + 2, g * 4 + 3, kcol), HG_U2(kt16, 16 + g * 4 + 0, 16 + g * 4 + 1, kcol), HG_U2(kt16, 16 + g * 4 + 2, 16 + g * 4 + 3, kcol)});
;                   S[kt] = __builtin_amdgcn_mfma_f32_16x16x32_bf16(kl, vf, S[kt], 0, 0, 0) * dcy; }
	v_mfma_f32_16x16x32_bf16 v[88:91], v[182:185], v[186:189], v[88:91]
	v_mfma_f32_16x16x32_bf16 v[72:75], v[0:3], v[80:83], v[92:95]
	v_mfma_f32_16x16x32_bf16 v[84:87], v[84:87], v[80:83], v[88:91]
	s_nop 4
	s_nop 1
	v_cvt_pk_bf16_f32 v3, v72, s0
	ds_write_b16 v196, v3 offset:4608
	v_cvt_pk_bf16_f32 v3, v84, s0
	ds_write_b16 v196, v3 offset:6912
	v_cvt_pk_bf16_f32 v3, v73, s0
	ds_write_b16 v196, v3 offset:4752
	v_cvt_pk_bf16_f32 v3, v85, s0
	ds_write_b16 v196, v3 offset:7056
	v_cvt_pk_bf16_f32 v3, v74, s0
	ds_write_b16 v196, v3 offset:4896
	v_cvt_pk_bf16_f32 v3, v86, s0
	ds_write_b16 v196, v3 offset:7200
	v_cvt_pk_bf16_f32 v3, v75, s0
	ds_write_b16 v196, v3 offset:5040
	v_cvt_pk_bf16_f32 v3, v87, s0
	ds_write_b16 v196, v3 offset:7344
	ds_read_b128 v[72:75], v149 offset:58880
	ds_read_b64_tr_b16 v[200:201], v199 offset:50176
	ds_read_b64_tr_b16 v[202:203], v199 offset:54528
	ds_read_b64_tr_b16 v[204:205], v199 offset:50208
	ds_read_b64_tr_b16 v[206:207], v199 offset:54560
	ds_read_b64_tr_b16 v[208:209], v199 offset:50240
	ds_read_b64_tr_b16 v[210:211], v199 offset:54592
	ds_read_b64_tr_b16 v[212:213], v199 offset:50272
	ds_read_b64_tr_b16 v[214:215], v199 offset:54624
	ds_read_b64_tr_b16 v[216:217], v199 offset:50304
	ds_read_b64_tr_b16 v[218:219], v199 offset:54656
	ds_read_b64_tr_b16 v[220:221], v199 offset:50336
	ds_read_b64_tr_b16 v[222:223], v199 offset:54688
	ds_read_b64_tr_b16 v[224:225], v199 offset:50368
	ds_read_b64_tr_b16 v[226:227], v199 offset:54720
	ds_read_b64_tr_b16 v[228:229], v199 offset:50400
	ds_read_b64_tr_b16 v[230:231], v199 offset:54752
	s_waitcnt lgkmcnt(14)
	v_mfma_f32_16x16x32_bf16 v[44:47], v[200:203], v[80:83], v[44:47]
	ds_read_b128 v[84:87], v149 offset:58944
	s_waitcnt lgkmcnt(13)
	v_mfma_f32_16x16x32_bf16 v[48:51], v[204:207], v[80:83], v[48:51]
	s_nop 4
	v_mul_f32_e32 v46, v74, v46
	v_mul_f32_e32 v47, v75, v47
	v_mul_f32_e32 v44, v72, v44
	v_mul_f32_e32 v45, v73, v45
	ds_read_b128 v[72:75], v149 offset:59008
	s_waitcnt lgkmcnt(1)
	v_mul_f32_e32 v50, v86, v50
	v_mul_f32_e32 v51, v87, v51
	v_mul_f32_e32 v48, v84, v48
	v_mul_f32_e32 v49, v85, v49
	v_mfma_f32_16x16x32_bf16 v[52:55], v[208:211], v[80:83], v[52:55]
	ds_read_b128 v[84:87], v149 offset:59072
	v_mfma_f32_16x16x32_bf16 v[56:59], v[212:215], v[80:83], v[56:59]
	s_nop 4
	s_waitcnt lgkmcnt(1)
	v_mul_f32_e32 v54, v74, v54
	v_mul_f32_e32 v55, v75, v55
	v_mul_f32_e32 v52, v72, v52
	v_mul_f32_e32 v53, v73, v53
	ds_read_b128 v[72:75], v149 offset:59136
	s_waitcnt lgkmcnt(1)
	v_mul_f32_e32 v58, v86, v58
	v_mul_f32_e32 v59, v87, v59
	v_mul_f32_e32 v56, v84, v56
	v_mul_f32_e32 v57, v85, v57
	v_mfma_f32_16x16x32_bf16 v[60:63], v[216:219], v[80:83], v[60:63]
	ds_read_b128 v[84:87], v149 offset:59200
	v_mfma_f32_16x16x32_bf16 v[64:67], v[220:223], v[80:83], v[64:67]
	s_nop 4
	s_waitcnt lgkmcnt(1)
	v_mul_f32_e32 v62, v74, v62
	v_mul_f32_e32 v63, v75, v63
	v_mul_f32_e32 v60, v72, v60
	v_mul_f32_e32 v61, v73, v61
	ds_read_b128 v[72:75], v149 offset:59264
	s_waitcnt lgkmcnt(1)
	v_mul_f32_e32 v66, v86, v66
	v_mul_f32_e32 v67, v87, v67
	v_mul_f32_e32 v64, v84, v64
	v_mul_f32_e32 v65, v85, v65
	v_mfma_f32_16x16x32_bf16 v[68:71], v[224:227], v[80:83], v[68:71]
	ds_read_b128 v[84:87], v149 offset:59328
	s_nop 5
	s_waitcnt lgkmcnt(1)
	v_mul_f32_e32 v74, v74, v70
	v_mul_f32_e32 v75, v75, v71
	v_mul_f32_e32 v72, v72, v68
	v_mul_f32_e32 v73, v73, v69
	v_mfma_f32_16x16x32_bf16 v[68:71], v[228:231], v[80:83], v[76:79]
	s_nop 6
	s_waitcnt lgkmcnt(0)
	v_mul_f32_e32 v70, v86, v70
	v_mul_f32_e32 v71, v87, v71
	v_mul_f32_e32 v68, v84, v68
	v_mul_f32_e32 v69, v85, v69
	s_cbranch_vccnz .Lscanc_exit
	s_mov_b32 s76, s75
	s_branch .LBB0_2417
.Lscanc_exit:
	s_waitcnt lgkmcnt(0)
	s_barrier
	s_branch .LBB0_2411
.Lscanh_pro:
	v_cmp_gt_u32_e32 vcc, 0x120, v252
	s_mov_b64 s[2:3], vcc
	s_and_b32 s101, s48, 32
	s_sub_u32 s101, s101, 16
	v_add_u32_e32 v228, 0xffffef00, v158
	v_add_u32_e32 v229, 0xfffff000, v159
	v_and_b32_e32 v97, 0xff, v252
	v_lshrrev_b32_e32 v98, 3, v97
	v_and_b32_e32 v97, 7, v97
	v_mul_u32_u24_e32 v96, 0x90, v98
	v_lshl_add_u32 v96, v97, 4, v96
	v_add_u32_e32 v96, 0x1a200, v96
	v_lshlrev_b32_e32 v94, 11, v98
	v_sub_u32_e32 v99, 0, v94
	v_cndmask_b32_e64 v94, v99, v94, s[12:13]
	v_lshl_add_u32 v94, v97, 4, v94
	s_lshl_b32 s14, s99, 7
	v_add_u32_e32 v94, s14, v94
	v_ashrrev_i32_e32 v95, 31, v94
	v_add_co_u32_e32 v250, vcc, 0xffffc000, v144
	s_nop 1
	v_addc_co_u32_e32 v251, vcc, -1, v145, vcc
	v_cndmask_b32_e64 v0, v150, v113, s[12:13]
	v_add_u32_e32 v0, s101, v0
	v_ashrrev_i32_e32 v1, 31, v0
	v_lshl_add_u64 v[0:1], s[50:51], 0, v[0:1]
	v_lshlrev_b64 v[196:197], 12, v[0:1]
	v_lshlrev_b64 v[0:1], 11, v[0:1]
	v_lshl_add_u64 v[198:199], v[128:129], 0, v[0:1]
	v_lshl_add_u64 v[208:209], v[142:143], 0, v[196:197]
	v_lshl_add_u64 v[0:1], v[130:131], 0, v[0:1]
	global_load_dwordx4 v[196:199], v[198:199], off
	s_nop 0
	global_load_dwordx4 v[200:203], v[208:209], off
	global_load_dwordx4 v[204:207], v[0:1], off
	s_nop 0
	global_load_dwordx4 v[208:211], v[208:209], off offset:2048
	s_and_saveexec_b64 s[14:15], s[2:3]
	s_cbranch_execz .Lscanh_ep0
	global_load_dwordx4 v[4:7], v[250:251], off

.Lscanh_ep1:
	s_or_b64 exec, exec, s[14:15]
	v_add_co_u32_e32 v250, vcc, 0x1000, v250
	s_nop 1
	v_addc_co_u32_e32 v251, vcc, 0, v251, vcc
	s_waitcnt vmcnt(0)
.Lscanh_loop:
	s_waitcnt vmcnt(9)
	v_lshlrev_b32_e32 v80, 16, v12
	v_and_b32_e32 v81, 0xffff0000, v12
	v_lshlrev_b32_e32 v82, 16, v16
	v_and_b32_e32 v83, 0xffff0000, v16
	v_lshlrev_b32_e32 v84, 16, v13
	v_and_b32_e32 v85, 0xffff0000, v13
	v_lshlrev_b32_e32 v86, 16, v17
	v_and_b32_e32 v87, 0xffff0000, v17
	v_mul_f32_e32 v80, v80, v82
	v_mul_f32_e32 v81, v81, v83
	v_mul_f32_e32 v84, v84, v86
	v_mul_f32_e32 v85, v85, v87
	v_cvt_pk_bf16_f32 v76, v80, v81
	v_cvt_pk_bf16_f32 v77, v84, v85
	v_lshlrev_b32_e32 v80, 16, v14
	v_and_b32_e32 v81, 0xffff0000, v14
	v_lshlrev_b32_e32 v82, 16, v18
	v_and_b32_e32 v83, 0xffff0000, v18
	v_lshlrev_b32_e32 v84, 16, v15
	v_and_b32_e32 v85, 0xffff0000, v15
	v_lshlrev_b32_e32 v86, 16, v19
	v_and_b32_e32 v87, 0xffff0000, v19
	v_mul_f32_e32 v80, v80, v82
	v_mul_f32_e32 v81, v81, v83
	v_mul_f32_e32 v84, v84, v86
	v_mul_f32_e32 v85, v85, v87
	v_cvt_pk_bf16_f32 v78, v80, v81
	v_cvt_pk_bf16_f32 v79, v84, v85
	v_lshlrev_b32_e32 v80, 16, v196
	v_and_b32_e32 v81, 0xffff0000, v196
	v_lshlrev_b32_e32 v82, 16, v200
	v_and_b32_e32 v83, 0xffff0000, v200
	v_lshlrev_b32_e32 v84, 16, v197
	v_and_b32_e32 v85, 0xffff0000, v197
	v_lshlrev_b32_e32 v86, 16, v201
	v_and_b32_e32 v87, 0xffff0000, v201
	v_mul_f32_e32 v80, v80, v82
	v_mul_f32_e32 v81, v81, v83
	v_mul_f32_e32 v84, v84, v86
	v_mul_f32_e32 v85, v85, v87
	v_cvt_pk_bf16_f32 v246, v80, v81
	v_cvt_pk_bf16_f32 v247, v84, v85
	v_lshlrev_b32_e32 v80, 16, v198
	v_and_b32_e32 v81, 0xffff0000, v198
	v_lshlrev_b32_e32 v82, 16, v202
	v_and_b32_e32 v83, 0xffff0000, v202
	v_lshlrev_b32_e32 v84, 16, v199
	v_and_b32_e32 v85, 0xffff0000, v199
	v_lshlrev_b32_e32 v86, 16, v203
	v_and_b32_e32 v87, 0xffff0000, v203
	v_mul_f32_e32 v80, v80, v82
	v_mul_f32_e32 v81, v81, v83
	v_mul_f32_e32 v84, v84, v86
	v_mul_f32_e32 v85, v85, v87
	v_cvt_pk_bf16_f32 v248, v80, v81
	v_cvt_pk_bf16_f32 v249, v84, v85
	ds_write_b128 v158, v[76:79]
	ds_write_b128 v158, v[20:23] offset:8704
	ds_write_b128 v158, v[24:27] offset:17408
	ds_write_b128 v228, v[246:249]
	ds_write_b128 v228, v[204:207] offset:8704
	ds_write_b128 v228, v[208:211] offset:17408
	s_and_saveexec_b64 s[14:15], s[2:3]
	ds_write_b128 v229, v[4:7] offset:26112
	s_or_b64 exec, exec, s[14:15]
	s_add_i32 s75, s76, 2
	s_cmpk_lt_u32 s76, 0x46
	s_cselect_b64 s[56:57], -1, 0
	s_cmpk_gt_u32 s76, 0x45
	s_cselect_b64 s[54:55], -1, 0
	s_waitcnt lgkmcnt(0)
	s_barrier
	s_cmp_eq_u32 s76, 0
	s_cbranch_scc1 .Lscanh_nordb
	ds_read_b128 v[88:91], v96 offset:4608
.Lscanh_nordb:
	s_and_b64 vcc, exec, s[54:55]
	s_cbranch_vccnz .Lscanh_nopfa
	s_and_b64 vcc, exec, s[12:13]
	v_lshl_add_u32 v0, s75, 5, v113
	s_cbranch_vccnz .Lscanh_ia
	v_add3_u32 v1, v113, s74, 64
	v_cmp_lt_i32_e32 vcc, s47, v1
	s_and_saveexec_b64 s[14:15], vcc
	s_xor_b64 s[14:15], exec, s[14:15]
	v_add_u32_e32 v0, s38, v156
	v_add_u32_e32 v0, 0x9df, v0
	s_andn2_saveexec_b64 s[14:15], s[14:15]
	v_sub_u32_e32 v0, 0xff, v0
	s_or_b64 exec, exec, s[14:15]

; DI unsigned pack2(float lo, float hi) { const f32x2 v = (f32x2){lo, hi}; return __builtin_bit_cast(unsigned, __builtin_convertvector(v, bf16x2_t)); }
; DI void hgrn_scan_mfma(const Params& p, char* shm) {
;     ...
; #pragma unroll
;               for (int r = 0; r < 4; ++r) {
;                   const long rb_ = (long)HG_ROW(b, dir, ch * C), st_ = dir ? -(long)D : (long)D; bf16_t* op_ = Oo + rb_ * D + head * 128 + vcol + (long)(g * 4 + r) * st_;
;                   op_[0] = (bf16_t)(pack2(o0[r], 0.f) & 0xffffu); op_[16 * st_] = (bf16_t)(pack2(o1[r], 0.f) & 0xffffu); }
.Lscanh_nopfa:
	s_cmp_eq_u32 s76, 0
	s_cbranch_scc1 .Lscanh_nocpb
	s_mov_b32 s14, s77
	s_add_u32 s14, s50, s14
	s_addc_u32 s15, s51, 0
	s_lshl_b64 s[14:15], s[14:15], 11
	s_add_u32 s14, s14, s78
	s_addc_u32 s15, s15, s79
	s_waitcnt lgkmcnt(0)
	v_lshl_add_u64 v[92:93], v[94:95], 0, s[14:15]
	global_store_dwordx4 v[92:93], v[88:91], off

.Lscanh_steady:
	s_waitcnt vmcnt(9)
	v_lshlrev_b32_e32 v80, 16, v28
	v_and_b32_e32 v81, 0xffff0000, v28
	v_lshlrev_b32_e32 v82, 16, v32
	v_and_b32_e32 v83, 0xffff0000, v32
	v_lshlrev_b32_e32 v84, 16, v29
	v_and_b32_e32 v85, 0xffff0000, v29
	v_lshlrev_b32_e32 v86, 16, v33
	v_and_b32_e32 v87, 0xffff0000, v33
	v_mul_f32_e32 v80, v80, v82
	v_mul_f32_e32 v81, v81, v83
	v_mul_f32_e32 v84, v84, v86
	v_mul_f32_e32 v85, v85, v87
	v_cvt_pk_bf16_f32 v68, v80, v81
	v_cvt_pk_bf16_f32 v69, v84, v85
	v_lshlrev_b32_e32 v80, 16, v30
	v_and_b32_e32 v81, 0xffff0000, v30
	v_lshlrev_b32_e32 v82, 16, v34
	v_and_b32_e32 v83, 0xffff0000, v34
	v_lshlrev_b32_e32 v84, 16, v31
	v_and_b32_e32 v85, 0xffff0000, v31
	v_lshlrev_b32_e32 v86, 16, v35
	v_and_b32_e32 v87, 0xffff0000, v35
	v_mul_f32_e32 v80, v80, v82
	v_mul_f32_e32 v81, v81, v83
	v_mul_f32_e32 v84, v84, v86
	v_mul_f32_e32 v85, v85, v87
	v_cvt_pk_bf16_f32 v70, v80, v81
	v_cvt_pk_bf16_f32 v71, v84, v85
	v_lshlrev_b32_e32 v80, 16, v212
	v_and_b32_e32 v81, 0xffff0000, v212
	v_lshlrev_b32_e32 v82, 16, v216
	v_and_b32_e32 v83, 0xffff0000, v216
	v_lshlrev_b32_e32 v84, 16, v213
	v_and_b32_e32 v85, 0xffff0000, v213
	v_lshlrev_b32_e32 v86, 16, v217
	v_and_b32_e32 v87, 0xffff0000, v217
	v_mul_f32_e32 v80, v80, v82
	v_mul_f32_e32 v81, v81, v83
	v_mul_f32_e32 v84, v84, v86
	v_mul_f32_e32 v85, v85, v87
	v_cvt_pk_bf16_f32 v246, v80, v81
	v_cvt_pk_bf16_f32 v247, v84, v85
	v_lshlrev_b32_e32 v80, 16, v214
	v_and_b32_e32 v81, 0xffff0000, v214
	v_lshlrev_b32_e32 v82, 16, v218
	v_and_b32_e32 v83, 0xffff0000, v218
	v_lshlrev_b32_e32 v84, 16, v215
	v_and_b32_e32 v85, 0xffff0000, v215
	v_lshlrev_b32_e32 v86, 16, v219
	v_and_b32_e32 v87, 0xffff0000, v219
	v_mul_f32_e32 v80, v80, v82
	v_mul_f32_e32 v81, v81, v83
	v_mul_f32_e32 v84, v84, v86
	v_mul_f32_e32 v85, v85, v87
	v_cvt_pk_bf16_f32 v248, v80, v81
	v_cvt_pk_bf16_f32 v249, v84, v85
	ds_write_b128 v158, v[68:71] offset:32768
	ds_write_b128 v158, v[36:39] offset:41472
	ds_write_b128 v158, v[40:43] offset:50176
	ds_write_b128 v228, v[246:249] offset:32768
	ds_write_b128 v228, v[220:223] offset:41472
	ds_write_b128 v228, v[224:227] offset:50176
	s_and_saveexec_b64 s[14:15], s[2:3]
	ds_write_b128 v229, v[8:11] offset:58880
	s_or_b64 exec, exec, s[14:15]
	s_waitcnt lgkmcnt(0)
	s_barrier
	ds_read_b128 v[88:91], v96 offset:0
	s_andn2_b64 vcc, exec, s[56:57]
	s_cbranch_vccnz .Lscanh_nopfb
	s_lshl_b32 s14, s76, 5
	s_addk_i32 s14, 0x60
	s_and_b64 vcc, exec, s[12:13]
	v_add_u32_e32 v0, s14, v113
	s_cbranch_vccnz .Lscanh_ib
	v_add_u32_e32 v1, s74, v113
	v_add_u32_e32 v1, 0x60, v1
	v_cmp_lt_i32_e32 vcc, s47, v1
	s_and_saveexec_b64 s[14:15], vcc
	s_xor_b64 s[14:15], exec, s[14:15]
	v_add_u32_e32 v0, s38, v156
	v_add_u32_e32 v0, 0x9bf, v0
	s_andn2_saveexec_b64 s[14:15], s[14:15]
	v_sub_u32_e32 v0, 0xff, v0
	s_or_b64 exec, exec, s[14:15]

; DI unsigned pack2(float lo, float hi) { const f32x2 v = (f32x2){lo, hi}; return __builtin_bit_cast(unsigned, __builtin_convertvector(v, bf16x2_t)); }
; DI void hgrn_scan_mfma(const Params& p, char* shm) {
;     ...
; #pragma unroll
;               for (int r = 0; r < 4; ++r) {
;                   const long rb_ = (long)HG_ROW(b, dir, ch * C), st_ = dir ? -(long)D : (long)D; bf16_t* op_ = Oo + rb_ * D + head * 128 + vcol + (long)(g * 4 + r) * st_;
;                   op_[0] = (bf16_t)(pack2(o0[r], 0.f) & 0xffffu); op_[16 * st_] = (bf16_t)(pack2(o1[r], 0.f) & 0xffffu); }
.Lscanh_nopfb:
	s_cmp_lt_u32 s76, 8
	s_cselect_b32 s14, 0xff, s58
	s_add_i32 s14, s14, s38
	s_add_i32 s14, s14, 32
	s_and_b64 vcc, s[12:13], exec
	s_cselect_b32 s14, s74, s14
	s_add_u32 s14, s50, s14
	s_addc_u32 s15, s51, 0
	s_lshl_b64 s[14:15], s[14:15], 11
	s_add_u32 s14, s14, s78
	s_addc_u32 s15, s15, s79
	s_waitcnt lgkmcnt(0)
	v_lshl_add_u64 v[92:93], v[94:95], 0, s[14:15]
	global_store_dwordx4 v[92:93], v[88:91], off
	s_cmp_lt_u32 s76, 8
	s_cselect_b32 s77, 0xff, s58
	s_add_i32 s77, s77, s38
	s_add_i32 s15, s74, 32
	s_and_b64 vcc, s[12:13], exec
	s_cselect_b32 s77, s15, s77
	s_sub_i32 s38, s38, 64
	s_add_i32 s74, s74, 64
	s_and_b64 vcc, exec, s[54:55]
	s_cbranch_vccnz .Lscanh_exit
	s_mov_b32 s76, s75
	s_branch .Lscanh_loop
.Lscanh_exit:
	s_barrier
	ds_read_b128 v[88:91], v96 offset:4608
	s_mov_b32 s14, s77
	s_add_u32 s14, s50, s14
	s_addc_u32 s15, s51, 0
	s_lshl_b64 s[14:15], s[14:15], 11
	s_add_u32 s14, s14, s78
	s_addc_u32 s15, s15, s79
	s_waitcnt lgkmcnt(0)
	v_lshl_add_u64 v[92:93], v[94:95], 0, s[14:15]
	global_store_dwordx4 v[92:93], v[88:91], off
	s_branch .LBB0_2411
